# FFN pre-norm row loop software-pipelined: next row's loads issued before the current row's math/stores, counted vmcnt so store completion is off the critical path
# baseline (speedup 1.0000x reference)
; __device__ __forceinline__ float bf_lo(unsigned w) { return __uint_as_float(w << 16); }
; __device__ __forceinline__ float bf_hi(unsigned w) { return __uint_as_float(w & 0xffff0000u); }
; template <int MODE, bool INBF> ...
;     ...
;         for (int i0 = 0; i0 < 8; i0 += RB) {
;             f32x4 v[RB][8];
; #pragma unroll
;             for (int q = 0; q < RB; ++q) { const int row = blk * 64 + wave + 8 * (i0 + q);
;                 if (INBF) { const u32x2* xr = (const u32x2*)((const bf16*)xin_ + (size_t)row * DM) + lane;
; #pragma unroll
;                     for (int j = 0; j < 8; ++j) { const u32x2 w = xr[64 * j]; v[q][j] = (f32x4){bf_lo(w.x), bf_hi(w.x), bf_lo(w.y), bf_hi(w.y)}; }
;                 } else { const f32x4* xr = (const f32x4*)((const float*)xin_ + (size_t)row * DM) + lane;
; #pragma unroll
;                     for (int j = 0; j < 8; ++j) v[q][j] = xr[64 * j]; } }
; #pragma unroll
;             for (int q = 0; q < RB; ++q) { const int row = blk * 64 + wave + 8 * (i0 + q); float ss = 0.f;
; #pragma unroll
;                 for (int j = 0; j < 8; ++j) ss += (v[q][j].x * v[q][j].x + v[q][j].y * v[q][j].y) + (v[q][j].z * v[q][j].z + v[q][j].w * v[q][j].w);
;                 const float rstd = 1.0f / sqrtf(wave_sum(ss) * (1.0f / DM) + EPS);
.LBB0_417:
	s_or_b64 exec, exec, s[8:9]
	s_ashr_i32 s11, s10, 31
	s_lshl_b64 s[8:9], s[10:11], 12
	v_lshl_add_u64 v[58:59], v[56:57], 0, s[8:9]
	s_mov_b64 s[14:15], 0
	s_waitcnt lgkmcnt(0)
	s_barrier
	v_add_co_u32_e32 v216, vcc, 0x27400000, v58
	s_nop 1
	v_addc_co_u32_e32 v217, vcc, 0, v59, vcc
	global_load_dwordx2 v[200:201], v[216:217], off offset:1536
	global_load_dwordx2 v[202:203], v[216:217], off offset:3584
	global_load_dwordx2 v[204:205], v[216:217], off
	global_load_dwordx2 v[206:207], v[216:217], off offset:512
	global_load_dwordx2 v[208:209], v[216:217], off offset:1024
	global_load_dwordx2 v[210:211], v[216:217], off offset:2048
	global_load_dwordx2 v[212:213], v[216:217], off offset:2560
	global_load_dwordx2 v[214:215], v[216:217], off offset:3072
	s_waitcnt vmcnt(0)
.LBB0_418:
	v_lshl_add_u64 v[60:61], v[58:59], 0, s[14:15]
	v_add_co_u32_e32 v86, vcc, 0x27400000, v60
	v_add_co_u32_e64 v88, s[8:9], s19, v60
	s_nop 0
	v_addc_co_u32_e32 v87, vcc, 0, v61, vcc
	ds_read_b128 v[0:3], v68
	ds_read_b128 v[4:7], v68 offset:1024
	ds_read_b128 v[12:15], v68 offset:8192
	ds_read_b128 v[8:11], v68 offset:9216
	ds_read_b128 v[16:19], v68 offset:2048
	ds_read_b128 v[20:23], v68 offset:3072
	ds_read_b128 v[28:31], v68 offset:10240
	ds_read_b128 v[24:27], v68 offset:11264
	ds_read_b128 v[32:35], v68 offset:4096
	ds_read_b128 v[36:39], v68 offset:5120
	ds_read_b128 v[44:47], v68 offset:12288
	ds_read_b128 v[40:43], v68 offset:13312
	ds_read_b128 v[48:51], v68 offset:6144
	ds_read_b128 v[74:77], v68 offset:7168
	ds_read_b128 v[78:81], v68 offset:14336
	ds_read_b128 v[82:85], v68 offset:15360
	v_addc_co_u32_e64 v89, s[8:9], 0, v61, s[8:9]
	s_add_u32 s14, s14, 0x8000
	s_addc_u32 s15, s15, 0
	s_cmp_lg_u32 s14, 0x40000
	s_waitcnt vmcnt(8) lgkmcnt(0)
	v_mov_b32_e32 v60, v200
	v_mov_b32_e32 v61, v201
	v_mov_b32_e32 v90, v202
	v_mov_b32_e32 v91, v203
	v_mov_b32_e32 v92, v204
	v_mov_b32_e32 v93, v205
	v_mov_b32_e32 v94, v206
	v_mov_b32_e32 v95, v207
	v_mov_b32_e32 v96, v208
	v_mov_b32_e32 v97, v209
	v_mov_b32_e32 v98, v210
	v_mov_b32_e32 v99, v211
	v_mov_b32_e32 v100, v212
	v_mov_b32_e32 v101, v213
	v_mov_b32_e32 v102, v214
	v_mov_b32_e32 v103, v215
	s_cbranch_scc0 .Lnp_skip_nf0
	v_add_co_u32_e32 v216, vcc, 0x8000, v86
	s_nop 1
	v_addc_co_u32_e32 v217, vcc, 0, v87, vcc
	global_load_dwordx2 v[200:201], v[216:217], off offset:1536
	global_load_dwordx2 v[202:203], v[216:217], off offset:3584
	global_load_dwordx2 v[204:205], v[216:217], off
	global_load_dwordx2 v[206:207], v[216:217], off offset:512
	global_load_dwordx2 v[208:209], v[216:217], off offset:1024
	global_load_dwordx2 v[210:211], v[216:217], off offset:2048
	global_load_dwordx2 v[212:213], v[216:217], off offset:2560
	global_load_dwordx2 v[214:215], v[216:217], off offset:3072
.Lnp_skip_nf0:
	v_lshlrev_b32_e32 v87, 16, v60
	v_lshlrev_b32_e32 v107, 16, v90
	v_lshlrev_b32_e32 v110, 16, v92
	v_and_b32_e32 v111, 0xffff0000, v92
	v_lshlrev_b32_e32 v92, 16, v93
	v_and_b32_e32 v93, 0xffff0000, v93
	v_lshlrev_b32_e32 v113, 16, v95
	v_lshlrev_b32_e32 v112, 16, v94
	v_and_b32_e32 v95, 0xffff0000, v95
	v_and_b32_e32 v94, 0xffff0000, v94
	v_and_b32_e32 v115, 0xffff0000, v96
	v_mul_f32_e32 v86, v93, v93
	v_pk_mul_f32 v[122:123], v[94:95], v[94:95]
	v_mul_f32_e32 v106, v111, v111
	v_lshlrev_b32_e32 v114, 16, v96
	v_lshlrev_b32_e32 v96, 16, v97
	v_and_b32_e32 v97, 0xffff0000, v97
	v_mov_b32_e32 v125, v87
	v_mul_f32_e32 v124, v115, v115
	v_mov_b32_e32 v136, v112
	v_mov_b32_e32 v137, v94
	v_mov_b32_e32 v94, v113
	v_pk_fma_f32 v[142:143], v[92:93], v[92:93], v[86:87] op_sel_hi:[1,1,0]
	v_pk_fma_f32 v[112:113], v[112:113], v[112:113], v[122:123]
	v_pk_fma_f32 v[122:123], v[110:111], v[110:111], v[106:107] op_sel_hi:[1,1,0]
	v_and_b32_e32 v105, 0xffff0000, v60
	v_lshlrev_b32_e32 v60, 16, v61
	v_and_b32_e32 v61, 0xffff0000, v61
	v_mul_f32_e32 v126, v97, v97
	v_mov_b32_e32 v127, v107
	v_pk_fma_f32 v[144:145], v[114:115], v[114:115], v[124:125] op_sel_hi:[1,1,0]
	v_mov_b32_e32 v86, v122
	v_mov_b32_e32 v124, v142
	v_mul_f32_e32 v133, v105, v105
	v_mul_f32_e32 v135, v60, v60
	v_mul_f32_e32 v148, v61, v61
	v_mov_b32_e32 v104, v87
	v_pk_fma_f32 v[146:147], v[96:97], v[96:97], v[126:127] op_sel_hi:[1,1,0]
	v_pk_add_f32 v[122:123], v[122:123], v[142:143]
	v_pk_add_f32 v[112:113], v[112:113], v[112:113] op_sel:[0,1] op_sel_hi:[1,0]
	v_pk_mul_f32 v[86:87], v[86:87], v[124:125]
	v_lshlrev_b32_e32 v117, 16, v99
	v_lshlrev_b32_e32 v116, 16, v98
	v_and_b32_e32 v99, 0xffff0000, v99
	v_and_b32_e32 v98, 0xffff0000, v98
	v_mov_b32_e32 v145, v135
	v_mov_b32_e32 v147, v148
	v_mov_b32_e32 v113, v133
	v_mov_b32_e32 v123, v87
	v_pk_mul_f32 v[128:129], v[98:99], v[98:99]
	v_pk_add_f32 v[124:125], v[144:145], v[146:147]
	v_pk_add_f32 v[86:87], v[122:123], v[112:113]
	v_lshlrev_b32_e32 v119, 16, v101
	v_lshlrev_b32_e32 v118, 16, v100
	v_and_b32_e32 v101, 0xffff0000, v101
	v_and_b32_e32 v100, 0xffff0000, v100
	v_mov_b32_e32 v138, v116
	v_mov_b32_e32 v139, v98
	v_mov_b32_e32 v98, v117
	v_pk_fma_f32 v[116:117], v[116:117], v[116:117], v[128:129]
	v_pk_add_f32 v[86:87], v[86:87], v[124:125]
	v_lshlrev_b32_e32 v120, 16, v102
	v_and_b32_e32 v121, 0xffff0000, v102
	v_lshlrev_b32_e32 v102, 16, v103
	v_and_b32_e32 v103, 0xffff0000, v103
	v_pk_mul_f32 v[130:131], v[100:101], v[100:101]
	v_pk_add_f32 v[116:117], v[116:117], v[116:117] op_sel:[0,1] op_sel_hi:[1,0]
	v_pk_add_f32 v[86:87], v[86:87], v[86:87] op_sel:[0,1] op_sel_hi:[1,0]
	v_and_b32_e32 v109, 0xffff0000, v90
	v_lshlrev_b32_e32 v90, 16, v91
	v_and_b32_e32 v91, 0xffff0000, v91
	v_mul_f32_e32 v132, v121, v121
	v_mul_f32_e32 v134, v103, v103
	v_mov_b32_e32 v140, v118
	v_mov_b32_e32 v141, v100
	v_mov_b32_e32 v100, v119
	v_pk_fma_f32 v[118:119], v[118:119], v[118:119], v[130:131]
	v_mov_b32_e32 v126, v116
	v_mov_b32_e32 v106, v86
	v_mul_f32_e32 v149, v109, v109
	v_mul_f32_e32 v150, v90, v90
	v_mul_f32_e32 v151, v91, v91
	v_mov_b32_e32 v108, v107
	v_pk_fma_f32 v[128:129], v[120:121], v[120:121], v[132:133] op_sel_hi:[1,1,0]
	v_pk_fma_f32 v[130:131], v[102:103], v[102:103], v[134:135] op_sel_hi:[1,1,0]
	v_pk_add_f32 v[118:119], v[118:119], v[118:119] op_sel:[0,1] op_sel_hi:[1,0]
	v_pk_add_f32 v[86:87], v[86:87], v[116:117]
	v_pk_mul_f32 v[106:107], v[106:107], v[126:127]
	v_mov_b32_e32 v129, v150
	v_mov_b32_e32 v131, v151
	v_mov_b32_e32 v119, v149
	v_mov_b32_e32 v87, v107
	v_pk_add_f32 v[128:129], v[128:129], v[130:131]
	v_pk_add_f32 v[86:87], v[86:87], v[118:119]
	s_nop 0
	v_pk_add_f32 v[86:87], v[86:87], v[128:129]
	s_nop 0
	v_add_f32_e32 v86, v86, v87
	s_nop 0
	s_waitcnt lgkmcnt(0)
; #define LAS __attribute__((address_space(3)))
; __device__ __forceinline__ unsigned pk_bf16(float lo, float hi) { unsigned r; asm volatile("v_cvt_pk_bf16_f32 %0, %1, %2" : "=v"(r) : "v"(lo), "v"(hi)); return r; }
; template <int MODE, bool INBF> ...
;     ...
;             for (int q = 0; q < RB; ++q) { const int row = blk * 64 + wave + 8 * (i0 + q); float ss = 0.f;
; #pragma unroll
;                 for (int j = 0; j < 8; ++j) ss += (v[q][j].x * v[q][j].x + v[q][j].y * v[q][j].y) + (v[q][j].z * v[q][j].z + v[q][j].w * v[q][j].w);
;                 const float rstd = 1.0f / sqrtf(wave_sum(ss) * (1.0f / DM) + EPS);
; #pragma unroll
;                 for (int j = 0; j < 8; ++j) { const f32x4 a = *(const LAS f32x4*)(cA + 4 * (64 * j + lane)), bb = *(const LAS f32x4*)(cB + 4 * (64 * j + lane)); v[q][j] = (v[q][j] * rstd) * a + bb; }
;                 if (MODE == 1) { f32x4* o = (f32x4*)(outf + (size_t)row * DM) + lane;
; #pragma unroll
;                     for (int j = 0; j < 8; ++j) o[64 * j] = v[q][j];
;                 } else { u32x2* o = (u32x2*)(outb + (size_t)row * DM) + lane;
; #pragma unroll
;                     for (int j = 0; j < 8; ++j) { u32x2 w; w.x = pk_bf16(v[q][j].x, v[q][j].y); w.y = pk_bf16(v[q][j].z, v[q][j].w); o[64 * j] = w; } } }
	s_nop 1
	v_add_f32_dpp v86, v86, v86 quad_perm:[1,0,3,2] row_mask:0xf bank_mask:0xf
	s_nop 0
	s_waitcnt lgkmcnt(0)
	s_nop 1
	v_add_f32_dpp v86, v86, v86 quad_perm:[2,3,0,1] row_mask:0xf bank_mask:0xf
	s_nop 0
	s_waitcnt lgkmcnt(0)
	s_nop 1
	v_add_f32_dpp v86, v86, v86 row_half_mirror row_mask:0xf bank_mask:0xf
	s_nop 0
	s_waitcnt lgkmcnt(0)
	s_nop 1
	v_add_f32_dpp v86, v86, v86 row_mirror row_mask:0xf bank_mask:0xf
	v_mov_b32_e32 v87, v86
	s_waitcnt lgkmcnt(0)
	s_nop 1
	v_permlane16_swap_b32_e32 v86, v87
	v_add_f32_e32 v86, v86, v87
	v_mov_b32_e32 v87, v86
	s_waitcnt lgkmcnt(0)
	s_nop 1
	v_permlane32_swap_b32_e32 v86, v87
	v_add_f32_e32 v86, v86, v87
	v_fmamk_f32 v86, v86, 0x3a000000, v71
	v_mul_f32_e32 v87, 0x4f800000, v86
	v_cmp_gt_f32_e32 vcc, s18, v86
	s_nop 1
	v_cndmask_b32_e32 v86, v86, v87, vcc
	v_sqrt_f32_e32 v87, v86
	s_nop 0
	v_add_u32_e32 v106, -1, v87
	v_add_u32_e32 v107, 1, v87
	v_fma_f32 v112, -v106, v87, v86
	v_fma_f32 v113, -v107, v87, v86
	v_cmp_ge_f32_e64 s[8:9], 0, v112
	s_nop 1
	v_cndmask_b32_e64 v87, v87, v106, s[8:9]
	v_cmp_lt_f32_e64 s[8:9], 0, v113
	s_nop 1
	v_cndmask_b32_e64 v87, v87, v107, s[8:9]
	v_mul_f32_e32 v106, 0x37800000, v87
	v_cndmask_b32_e32 v87, v87, v106, vcc
	v_cmp_class_f32_e32 vcc, v86, v72
	s_nop 1
	v_cndmask_b32_e32 v86, v87, v86, vcc
	v_div_scale_f32 v87, s[8:9], v86, v86, 1.0
	v_rcp_f32_e32 v107, v87
	v_div_scale_f32 v106, vcc, 1.0, v86, 1.0
	v_fma_f32 v112, -v87, v107, 1.0
	v_fmac_f32_e32 v107, v112, v107
	v_mul_f32_e32 v112, v106, v107
	v_fma_f32 v113, -v87, v112, v106
	v_fmac_f32_e32 v112, v113, v107
	v_fma_f32 v87, -v87, v112, v106
	v_div_fmas_f32 v87, v87, v107, v112
	v_div_fixup_f32 v86, v87, v86, 1.0
	v_pk_mul_f32 v[106:107], v[86:87], v[110:111] op_sel_hi:[0,1]
	v_pk_mul_f32 v[92:93], v[86:87], v[92:93] op_sel_hi:[0,1]
	v_pk_fma_f32 v[0:1], v[0:1], v[106:107], v[12:13]
	v_pk_mul_f32 v[110:111], v[86:87], v[136:137] op_sel_hi:[0,1]
	v_pk_mul_f32 v[94:95], v[86:87], v[94:95] op_sel_hi:[0,1]
	v_pk_fma_f32 v[2:3], v[2:3], v[92:93], v[14:15]
	v_cvt_pk_bf16_f32 v0, v0, v1
	v_pk_mul_f32 v[112:113], v[86:87], v[114:115] op_sel_hi:[0,1]
	v_cvt_pk_bf16_f32 v1, v2, v3
	v_pk_mul_f32 v[96:97], v[86:87], v[96:97] op_sel_hi:[0,1]
	v_pk_fma_f32 v[6:7], v[6:7], v[94:95], v[10:11]
	v_pk_fma_f32 v[4:5], v[4:5], v[110:111], v[8:9]
	global_store_dwordx2 v[88:89], v[0:1], off
	v_cvt_pk_bf16_f32 v0, v4, v5
	v_cvt_pk_bf16_f32 v1, v6, v7
	v_pk_mul_f32 v[104:105], v[104:105], v[86:87] op_sel_hi:[1,0]
	v_pk_mul_f32 v[60:61], v[60:61], v[86:87] op_sel_hi:[1,0]
	v_pk_fma_f32 v[8:9], v[18:19], v[96:97], v[30:31]
	v_pk_fma_f32 v[10:11], v[16:17], v[112:113], v[28:29]
	global_store_dwordx2 v[88:89], v[0:1], off offset:512
	v_cvt_pk_bf16_f32 v0, v10, v11
	v_cvt_pk_bf16_f32 v1, v8, v9
	v_pk_mul_f32 v[114:115], v[86:87], v[138:139] op_sel_hi:[0,1]
	v_pk_mul_f32 v[98:99], v[86:87], v[98:99] op_sel_hi:[0,1]
	v_pk_fma_f32 v[12:13], v[22:23], v[60:61], v[26:27]
	v_pk_fma_f32 v[14:15], v[20:21], v[104:105], v[24:25]
	global_store_dwordx2 v[88:89], v[0:1], off offset:1024
	v_cvt_pk_bf16_f32 v0, v14, v15
	v_cvt_pk_bf16_f32 v1, v12, v13
	v_pk_mul_f32 v[116:117], v[86:87], v[140:141] op_sel_hi:[0,1]
	v_pk_mul_f32 v[100:101], v[86:87], v[100:101] op_sel_hi:[0,1]
	v_pk_fma_f32 v[16:17], v[34:35], v[98:99], v[46:47]
	v_pk_fma_f32 v[18:19], v[32:33], v[114:115], v[44:45]
	global_store_dwordx2 v[88:89], v[0:1], off offset:1536
	v_cvt_pk_bf16_f32 v0, v18, v19
	v_cvt_pk_bf16_f32 v1, v16, v17
	v_pk_mul_f32 v[118:119], v[86:87], v[120:121] op_sel_hi:[0,1]
	v_pk_mul_f32 v[102:103], v[86:87], v[102:103] op_sel_hi:[0,1]
	v_pk_fma_f32 v[20:21], v[38:39], v[100:101], v[42:43]
	v_pk_fma_f32 v[22:23], v[36:37], v[116:117], v[40:41]
	global_store_dwordx2 v[88:89], v[0:1], off offset:2048
	v_cvt_pk_bf16_f32 v0, v22, v23
	v_cvt_pk_bf16_f32 v1, v20, v21
	v_pk_mul_f32 v[108:109], v[108:109], v[86:87] op_sel_hi:[1,0]
	v_pk_mul_f32 v[86:87], v[90:91], v[86:87] op_sel_hi:[1,0]
	v_pk_fma_f32 v[24:25], v[50:51], v[102:103], v[80:81]
	v_pk_fma_f32 v[26:27], v[48:49], v[118:119], v[78:79]
	global_store_dwordx2 v[88:89], v[0:1], off offset:2560
	v_cvt_pk_bf16_f32 v0, v26, v27
	v_cvt_pk_bf16_f32 v1, v24, v25
	v_pk_fma_f32 v[28:29], v[86:87], v[76:77], v[84:85]
	v_pk_fma_f32 v[30:31], v[108:109], v[74:75], v[82:83]
	global_store_dwordx2 v[88:89], v[0:1], off offset:3072
	v_cvt_pk_bf16_f32 v0, v30, v31
	v_cvt_pk_bf16_f32 v1, v28, v29
	global_store_dwordx2 v[88:89], v[0:1], off offset:3584
	s_cbranch_scc1 .LBB0_418
	s_add_i32 s20, s20, s3
	s_add_i32 s10, s10, s16
	s_cmpk_lt_i32 s20, 0x100
	s_cbranch_scc1 .LBB0_414
